# full stack: v67 + leader early invalidate + attention permlane shuffles + P2 load de-serialization + P5 residual prefetch + scan partial-sum batching
# speedup vs baseline: 1.0062x; 1.0057x over previous
.LBB0_550:
	s_andn2_saveexec_b64 s[10:11], s[10:11]
	s_cbranch_execz .LBB0_570
	buffer_inv sc1
	s_waitcnt lgkmcnt(0)
	s_cmp_lg_u32 s99, 0
	s_cbranch_scc1 .Lxcd_local_1
	s_mov_b64 s[10:11], exec
	buffer_wbl2 sc1
	s_waitcnt lgkmcnt(0)
	s_waitcnt vmcnt(0)
	v_mbcnt_lo_u32_b32 v1, s10, 0
	v_mbcnt_hi_u32_b32 v1, s11, v1
	v_cmp_eq_u32_e32 vcc, 0, v1
	s_and_saveexec_b64 s[12:13], vcc
	s_cbranch_execz .LBB0_553
	s_bcnt1_i32_b64 s10, s[10:11]
	v_mov_b32_e32 v2, 0x7000
	v_mov_b32_e32 v3, s10
	global_atomic_add v2, v2, v3, s[6:7] offset:1024 sc0

.Lxcd_local_1:
	s_mov_b64 s[6:7], exec
	v_mbcnt_lo_u32_b32 v0, s6, 0
	v_mbcnt_hi_u32_b32 v0, s7, v0
	v_cmp_eq_u32_e32 vcc, 0, v0
	s_and_saveexec_b64 s[10:11], vcc
	s_cbranch_execz .LBB0_569
	s_bcnt1_i32_b64 s6, s[6:7]
	v_mov_b32_e32 v0, 0x2000
	v_mov_b32_e32 v1, s6
	global_atomic_add v0, v1, s[8:9] offset:1024
